# k16 plus non-temporal attention output stores (O1/O2/OB single-use streams), P5 nt input loads, LDS unit table
# speedup vs baseline: 1.0035x; 1.0035x over previous
; #define SBAR() __builtin_amdgcn_sched_barrier(0)
; __device__ __forceinline__ int crow(int r, int hi) { return (r & 3) + 8 * (r >> 2) + 4 * hi; }
; __device__ __forceinline__ void finishSM(f32x16& p0, f32x16& p1, float alpha, float& l_reg, bf16x8& pa0, bf16x8& pa1, bf16x8& pa2, bf16x8& pa3) {
;     for (int r = 0; r < 16; ++r) p1[r] = __builtin_amdgcn_exp2f(p1[r]);
;     float ps = 0; for (int r = 0; r < 16; ++r) ps += p0[r]; for (int r = 0; r < 16; ++r) ps += p1[r];
;     { auto rr = __builtin_amdgcn_permlane32_swap(__float_as_uint(ps), __float_as_uint(ps), false, false);
;       ps = __uint_as_float(rr[0]) + __uint_as_float(rr[1]); }
;     l_reg = l_reg * alpha + ps;
;     ...
;     PK4(p0, 0, pa0); PK4(p0, 8, pa1); PK4(p1, 0, pa2); PK4(p1, 8, pa3);
; template <bool ROPE, bool ALIBI, int QP, int Q2P, int KP, int VP, int OP>
; __device__ __forceinline__ void attn_unit(const Unit& u, char* lds, const int wid) {
;     ...
;     finishSM(pA0, pA1, alA, l_reg, pa0, pa1, pa2, pa3); SBAR();
;     pv_tile<0>(o, vb0, pa0, pa1, pa2, pa3);
;     __builtin_amdgcn_s_setprio(0);
;     int lane2; asm volatile("v_mbcnt_lo_u32_b32 %0, -1, 0\n\tv_mbcnt_hi_u32_b32 %0, -1, %0" : "=v"(lane2));
;     const int r32e = lane2 & 31, hie = lane2 >> 5;
;     if (hie == 0) li_l[r32e] = l_reg; asm volatile("s_waitcnt lgkmcnt(0)" ::: "memory");
;     float rli[16];
; #pragma unroll
;     for (int r = 0; r < 16; ++r) rli[r] = __builtin_amdgcn_rcpf(li_l[crow(r, hie)]);
.LBB0_710:
	v_add_f32_e32 v0, 0, v154
	v_add_f32_e32 v0, v158, v0
	v_add_f32_e32 v0, v155, v0
	v_add_f32_e32 v0, v157, v0
	v_add_f32_e32 v0, v153, v0
	v_add_f32_e32 v0, v156, v0
	v_add_f32_e32 v0, v151, v0
	v_add_f32_e32 v0, v152, v0
	v_add_f32_e32 v0, v150, v0
	v_add_f32_e32 v0, v166, v0
	v_add_f32_e32 v0, v159, v0
	v_add_f32_e32 v0, v165, v0
	v_exp_f32_e32 v12, v134
	v_add_f32_e32 v0, v160, v0
	v_exp_f32_e32 v13, v135
	v_add_f32_e32 v0, v164, v0
	v_exp_f32_e32 v14, v146
	v_add_f32_e32 v0, v161, v0
	v_exp_f32_e32 v15, v147
	v_add_f32_e32 v0, v163, v0
	v_exp_f32_e32 v17, v136
	v_add_f32_e32 v0, v12, v0
	v_exp_f32_e32 v83, v137
	v_add_f32_e32 v0, v13, v0
	v_exp_f32_e32 v84, v142
	v_add_f32_e32 v0, v14, v0
	v_exp_f32_e32 v85, v143
	v_add_f32_e32 v0, v15, v0
	v_exp_f32_e32 v86, v144
	v_add_f32_e32 v0, v17, v0
	v_exp_f32_e32 v87, v145
	v_add_f32_e32 v0, v83, v0
	v_exp_f32_e32 v88, v148
	v_add_f32_e32 v0, v84, v0
	v_exp_f32_e32 v89, v149
	v_add_f32_e32 v0, v85, v0
	v_exp_f32_e32 v90, v138
	v_add_f32_e32 v0, v86, v0
	v_exp_f32_e32 v91, v139
	v_add_f32_e32 v0, v87, v0
	v_exp_f32_e32 v92, v140
	v_add_f32_e32 v0, v88, v0
	v_exp_f32_e32 v93, v141
	v_add_f32_e32 v0, v89, v0
	v_add_f32_e32 v0, v90, v0
	v_add_f32_e32 v0, v91, v0
	v_add_f32_e32 v0, v92, v0
	v_add_f32_e32 v0, v93, v0
	v_mov_b32_e32 v1, v0
	v_cvt_pk_bf16_f32 v4, v154, v158
	v_cvt_pk_bf16_f32 v5, v155, v157
	v_cvt_pk_bf16_f32 v6, v153, v156
	s_nop 1
	v_permlane32_swap_b32_e32 v0, v1
	v_cvt_pk_bf16_f32 v7, v151, v152
	v_permlane32_swap_b32_e32 v4, v6
	v_cvt_pk_bf16_f32 v8, v150, v166
	v_cvt_pk_bf16_f32 v9, v159, v165
	v_cvt_pk_bf16_f32 v10, v160, v164
	v_cvt_pk_bf16_f32 v11, v161, v163
	v_cvt_pk_bf16_f32 v12, v12, v13
	v_cvt_pk_bf16_f32 v13, v14, v15
	v_cvt_pk_bf16_f32 v14, v17, v83
	v_cvt_pk_bf16_f32 v15, v84, v85
	v_cvt_pk_bf16_f32 v84, v86, v87
	v_cvt_pk_bf16_f32 v85, v88, v89
	v_cvt_pk_bf16_f32 v86, v90, v91
	v_cvt_pk_bf16_f32 v87, v92, v93
	v_permlane32_swap_b32_e32 v5, v7
	v_permlane32_swap_b32_e32 v8, v10
	v_permlane32_swap_b32_e32 v9, v11
	v_permlane32_swap_b32_e32 v12, v14
	v_permlane32_swap_b32_e32 v13, v15
	v_permlane32_swap_b32_e32 v84, v86
	v_permlane32_swap_b32_e32 v85, v87
	ds_read_b64_tr_b16 v[88:89], v3 offset:0
	ds_read_b64_tr_b16 v[90:91], v3 offset:0x800
	ds_read_b64_tr_b16 v[92:93], v3 offset:0x1000
	ds_read_b64_tr_b16 v[94:95], v3 offset:0x1800
	ds_read_b64_tr_b16 v[96:97], v3 offset:0x2000
	ds_read_b64_tr_b16 v[98:99], v3 offset:0x2800
	ds_read_b64_tr_b16 v[100:101], v3 offset:0x3000
	ds_read_b64_tr_b16 v[102:103], v3 offset:0x3800
	s_waitcnt lgkmcnt(0)
	s_nop 0
	v_mfma_f32_32x32x16_bf16 v[18:33], v[4:7], v[88:91], v[18:33]
	ds_read_b64_tr_b16 v[88:89], v3 offset:0x200
	ds_read_b64_tr_b16 v[90:91], v3 offset:0xa00
	v_mfma_f32_32x32x16_bf16 v[18:33], v[8:11], v[92:95], v[18:33]
	ds_read_b64_tr_b16 v[92:93], v3 offset:0x1200
	ds_read_b64_tr_b16 v[94:95], v3 offset:0x1a00
	v_mfma_f32_32x32x16_bf16 v[18:33], v[12:15], v[96:99], v[18:33]
	ds_read_b64_tr_b16 v[96:97], v3 offset:0x2200
	ds_read_b64_tr_b16 v[98:99], v3 offset:0x2a00
	v_mfma_f32_32x32x16_bf16 v[18:33], v[84:87], v[100:103], v[18:33]
	ds_read_b64_tr_b16 v[100:101], v3 offset:0x3200
	ds_read_b64_tr_b16 v[102:103], v3 offset:0x3a00
	s_waitcnt lgkmcnt(0)
	v_mfma_f32_32x32x16_bf16 v[66:81], v[4:7], v[88:91], v[66:81]
	ds_read_b64_tr_b16 v[88:89], v3 offset:0x400
	ds_read_b64_tr_b16 v[90:91], v3 offset:0xc00
	v_mfma_f32_32x32x16_bf16 v[66:81], v[8:11], v[92:95], v[66:81]
	ds_read_b64_tr_b16 v[92:93], v3 offset:0x1400
	ds_read_b64_tr_b16 v[94:95], v3 offset:0x1c00
	v_mfma_f32_32x32x16_bf16 v[66:81], v[12:15], v[96:99], v[66:81]
	ds_read_b64_tr_b16 v[96:97], v3 offset:0x2400
	ds_read_b64_tr_b16 v[98:99], v3 offset:0x2c00
	v_mfma_f32_32x32x16_bf16 v[66:81], v[84:87], v[100:103], v[66:81]
	ds_read_b64_tr_b16 v[100:101], v3 offset:0x3400
	ds_read_b64_tr_b16 v[102:103], v3 offset:0x3c00
	s_waitcnt lgkmcnt(0)
	v_mfma_f32_32x32x16_bf16 v[50:65], v[4:7], v[88:91], v[50:65]
	ds_read_b64_tr_b16 v[88:89], v3 offset:0x600
	ds_read_b64_tr_b16 v[90:91], v3 offset:0xe00
	v_mfma_f32_32x32x16_bf16 v[50:65], v[8:11], v[92:95], v[50:65]
	ds_read_b64_tr_b16 v[92:93], v3 offset:0x1600
	ds_read_b64_tr_b16 v[94:95], v3 offset:0x1e00
	v_mfma_f32_32x32x16_bf16 v[50:65], v[12:15], v[96:99], v[50:65]
	ds_read_b64_tr_b16 v[96:97], v3 offset:0x2600
	ds_read_b64_tr_b16 v[98:99], v3 offset:0x2e00
	v_mfma_f32_32x32x16_bf16 v[50:65], v[84:87], v[100:103], v[50:65]
	ds_read_b64_tr_b16 v[100:101], v3 offset:0x3600
	ds_read_b64_tr_b16 v[102:103], v3 offset:0x3e00
	s_waitcnt lgkmcnt(0)
	v_mfma_f32_32x32x16_bf16 v[34:49], v[4:7], v[88:91], v[34:49]
	v_mfma_f32_32x32x16_bf16 v[34:49], v[8:11], v[92:95], v[34:49]
	v_mfma_f32_32x32x16_bf16 v[34:49], v[12:15], v[96:99], v[34:49]
	v_mfma_f32_32x32x16_bf16 v[34:49], v[84:87], v[100:103], v[34:49]
	s_setprio 0
	v_mbcnt_lo_u32_b32 v4, -1, 0
	v_mbcnt_hi_u32_b32 v4, -1, v4
	s_nop 0
	v_and_b32_e32 v3, 31, v4
	v_cmp_gt_u32_e32 vcc, 32, v4
	s_and_saveexec_b64 s[4:5], vcc
	v_add_f32_e32 v0, v0, v1
	v_fmac_f32_e32 v0, v206, v82
	v_lshl_add_u32 v1, v3, 2, s90
	ds_write_b32 v1, v0
	s_or_b64 exec, exec, s[4:5]
	v_ashrrev_i32_e32 v1, 5, v4
	s_waitcnt lgkmcnt(0)
	v_lshl_add_u32 v0, v1, 4, s90
	ds_read_b128 v[6:9], v0
	ds_read_b128 v[10:13], v0 offset:32
	s_lshl_b32 s4, s89, 12
	s_add_u32 s4, s69, s4
	s_addc_u32 s5, s44, 0
	s_waitcnt lgkmcnt(1)
	v_rcp_f32_e32 v17, v6
	v_rcp_f32_e32 v82, v7
	v_rcp_f32_e32 v83, v8
	v_rcp_f32_e32 v84, v9
	s_waitcnt lgkmcnt(0)
; __device__ __forceinline__ int crow(int r, int hi) { return (r & 3) + 8 * (r >> 2) + 4 * hi; }
; __device__ __forceinline__ unsigned cvtpk(float lo, float hi) { unsigned r; asm volatile("v_cvt_pk_bf16_f32 %0, %1, %2" : "=v"(r) : "v"(lo), "v"(hi)); return r; }
; template <int OP>
; __device__ __forceinline__ void store_o_tile(const f32x16* o, const float* rli, char* stg, bf16_t* Ow, int r32e, int hie, int lane2) {
; #pragma unroll
;     for (int hf = 0; hf < 2; ++hf) {
; #pragma unroll
;         for (int r = 0; r < 16; ++r) { const int orow = crow(r, hie);
; #pragma unroll
;             for (int d = 0; d < 2; ++d) { const float v = o[2 * hf + d][r] * rli[r]; *(unsigned short*)(stg + (orow * 64 + d * 32 + r32e) * 2) = (unsigned short)cvtpk(v, v); } }
;         asm volatile("s_waitcnt lgkmcnt(0)" ::: "memory");
; #pragma unroll
;         for (int i = 0; i < 4; ++i) { const int row = i * 8 + (lane2 >> 3), ch = lane2 & 7; const u32x4 w = *(const u32x4*)(stg + (row * 64 + ch * 8) * 2);
;             *(u32x4*)(Ow + (size_t)row * OP + hf * 64 + ch * 8) = w; }
;         asm volatile("s_waitcnt lgkmcnt(0)" ::: "memory"); }
	v_rcp_f32_e32 v85, v10
	ds_read_b128 v[6:9], v0 offset:64
	v_rcp_f32_e32 v86, v11
	v_rcp_f32_e32 v87, v12
	v_rcp_f32_e32 v88, v13
	ds_read_b128 v[10:13], v0 offset:96
	s_lshl_b32 s6, s88, 8
	s_add_u32 s4, s4, s6
	s_addc_u32 s5, s5, 0
	v_readlane_b32 s6, v254, 6
	v_readlane_b32 s7, v254, 7
	s_add_u32 s4, s4, s6
	v_ashrrev_i32_e32 v0, 3, v4
	v_lshlrev_b32_e32 v4, 4, v4
	s_waitcnt lgkmcnt(0)
	v_rcp_f32_e32 v95, v12
	v_rcp_f32_e32 v96, v13
	s_addc_u32 s5, s5, s7
	v_and_b32_e32 v12, 0x70, v4
	v_mov_b32_e32 v13, v2
	v_lshlrev_b32_e32 v4, 7, v0
	v_lshlrev_b32_e32 v1, 9, v1
	v_lshlrev_b32_e32 v3, 1, v3
	v_lshl_add_u64 v[14:15], s[4:5], 0, v[12:13]
	v_add3_u32 v13, s91, v4, v12
	v_mul_f32_e32 v4, v18, v17
	v_add3_u32 v3, s91, v1, v3
	v_mul_f32_e32 v1, v66, v17
	v_cvt_pk_bf16_f32 v4, v4, v4
	ds_write_b16 v3, v4 offset:32768
	v_cvt_pk_bf16_f32 v1, v1, v1
	ds_write_b16 v3, v1 offset:32832
	v_mul_f32_e32 v1, v19, v82
	v_cvt_pk_bf16_f32 v1, v1, v1
	ds_write_b16 v3, v1 offset:32896
	v_mul_f32_e32 v1, v67, v82
	v_cvt_pk_bf16_f32 v1, v1, v1
	ds_write_b16 v3, v1 offset:32960
	v_mul_f32_e32 v1, v20, v83
	v_cvt_pk_bf16_f32 v1, v1, v1
	ds_write_b16 v3, v1 offset:33024
	v_mul_f32_e32 v1, v68, v83
	v_cvt_pk_bf16_f32 v1, v1, v1
	ds_write_b16 v3, v1 offset:33088
	v_mul_f32_e32 v1, v21, v84
	v_cvt_pk_bf16_f32 v1, v1, v1
	ds_write_b16 v3, v1 offset:33152
	v_mul_f32_e32 v1, v69, v84
	v_cvt_pk_bf16_f32 v1, v1, v1
	ds_write_b16 v3, v1 offset:33216
	v_mul_f32_e32 v1, v22, v85
	v_cvt_pk_bf16_f32 v1, v1, v1
	ds_write_b16 v3, v1 offset:33792
	v_mul_f32_e32 v1, v70, v85
	v_cvt_pk_bf16_f32 v1, v1, v1
	ds_write_b16 v3, v1 offset:33856
	v_mul_f32_e32 v1, v23, v86
	v_cvt_pk_bf16_f32 v1, v1, v1
	ds_write_b16 v3, v1 offset:33920
	v_mul_f32_e32 v1, v71, v86
	v_cvt_pk_bf16_f32 v1, v1, v1
	ds_write_b16 v3, v1 offset:33984
	v_mul_f32_e32 v1, v24, v87
	v_cvt_pk_bf16_f32 v1, v1, v1
	ds_write_b16 v3, v1 offset:34048
	v_mul_f32_e32 v1, v72, v87
	v_cvt_pk_bf16_f32 v1, v1, v1
	v_rcp_f32_e32 v89, v6
	ds_write_b16 v3, v1 offset:34112
	v_mul_f32_e32 v1, v25, v88
	v_cvt_pk_bf16_f32 v1, v1, v1
	ds_write_b16 v3, v1 offset:34176
	v_mul_f32_e32 v1, v73, v88
	v_cvt_pk_bf16_f32 v1, v1, v1
	v_rcp_f32_e32 v90, v7
	ds_write_b16 v3, v1 offset:34240
	v_mul_f32_e32 v1, v26, v89
	v_cvt_pk_bf16_f32 v1, v1, v1
	ds_write_b16 v3, v1 offset:34816
	v_mul_f32_e32 v1, v74, v89
	v_cvt_pk_bf16_f32 v1, v1, v1
	v_rcp_f32_e32 v91, v8
	ds_write_b16 v3, v1 offset:34880
	v_mul_f32_e32 v1, v27, v90
	v_cvt_pk_bf16_f32 v1, v1, v1
	ds_write_b16 v3, v1 offset:34944
	v_mul_f32_e32 v1, v75, v90
	v_cvt_pk_bf16_f32 v1, v1, v1
	v_rcp_f32_e32 v92, v9
	ds_write_b16 v3, v1 offset:35008
	v_mul_f32_e32 v1, v28, v91
	v_cvt_pk_bf16_f32 v1, v1, v1
	ds_write_b16 v3, v1 offset:35072
	v_mul_f32_e32 v1, v76, v91
	v_cvt_pk_bf16_f32 v1, v1, v1
	v_rcp_f32_e32 v93, v10
	ds_write_b16 v3, v1 offset:35136
	v_mul_f32_e32 v1, v29, v92
	v_cvt_pk_bf16_f32 v1, v1, v1
	ds_write_b16 v3, v1 offset:35200
	v_mul_f32_e32 v1, v77, v92
	v_cvt_pk_bf16_f32 v1, v1, v1
	v_rcp_f32_e32 v94, v11
	ds_write_b16 v3, v1 offset:35264
	v_mul_f32_e32 v1, v30, v93
	v_cvt_pk_bf16_f32 v1, v1, v1
	ds_write_b16 v3, v1 offset:35840
	v_mul_f32_e32 v1, v78, v93
	v_cvt_pk_bf16_f32 v1, v1, v1
	ds_write_b16 v3, v1 offset:35904
	v_mul_f32_e32 v1, v31, v94
	v_cvt_pk_bf16_f32 v1, v1, v1
	ds_write_b16 v3, v1 offset:35968
	v_mul_f32_e32 v1, v79, v94
	v_cvt_pk_bf16_f32 v1, v1, v1
	ds_write_b16 v3, v1 offset:36032
	v_mul_f32_e32 v1, v32, v95
	v_cvt_pk_bf16_f32 v1, v1, v1
	ds_write_b16 v3, v1 offset:36096
	v_mul_f32_e32 v1, v80, v95
	v_cvt_pk_bf16_f32 v1, v1, v1
	ds_write_b16 v3, v1 offset:36160
	v_mul_f32_e32 v1, v33, v96
	v_cvt_pk_bf16_f32 v1, v1, v1
	ds_write_b16 v3, v1 offset:36224
	v_mul_f32_e32 v1, v81, v96
	v_cvt_pk_bf16_f32 v1, v1, v1
	ds_write_b16 v3, v1 offset:36288
	s_waitcnt lgkmcnt(0)
	v_ashrrev_i32_e32 v1, 31, v0
	v_add_u32_e32 v18, 8, v0
	ds_read_b128 v[4:7], v13 offset:32768
	v_lshlrev_b64 v[8:9], 12, v[0:1]
	v_lshlrev_b32_e32 v1, 7, v18
	v_add3_u32 v20, s91, v1, v12
	v_lshl_add_u64 v[22:23], v[14:15], 0, v[8:9]
	ds_read_b128 v[8:11], v20 offset:32768
	v_ashrrev_i32_e32 v19, 31, v18
	s_waitcnt lgkmcnt(1)
	global_store_dwordx4 v[22:23], v[4:7], off nt
	s_nop 1
	v_lshlrev_b64 v[4:5], 12, v[18:19]
	v_lshl_add_u64 v[24:25], v[14:15], 0, v[4:5]
	s_waitcnt lgkmcnt(0)
; __device__ __forceinline__ int crow(int r, int hi) { return (r & 3) + 8 * (r >> 2) + 4 * hi; }
; __device__ __forceinline__ unsigned cvtpk(float lo, float hi) { unsigned r; asm volatile("v_cvt_pk_bf16_f32 %0, %1, %2" : "=v"(r) : "v"(lo), "v"(hi)); return r; }
; template <int OP>
; __device__ __forceinline__ void store_o_tile(const f32x16* o, const float* rli, char* stg, bf16_t* Ow, int r32e, int hie, int lane2) {
; #pragma unroll
;     for (int hf = 0; hf < 2; ++hf) {
; #pragma unroll
;         for (int r = 0; r < 16; ++r) { const int orow = crow(r, hie);
; #pragma unroll
;             for (int d = 0; d < 2; ++d) { const float v = o[2 * hf + d][r] * rli[r]; *(unsigned short*)(stg + (orow * 64 + d * 32 + r32e) * 2) = (unsigned short)cvtpk(v, v); } }
;         asm volatile("s_waitcnt lgkmcnt(0)" ::: "memory");
; #pragma unroll
;         for (int i = 0; i < 4; ++i) { const int row = i * 8 + (lane2 >> 3), ch = lane2 & 7; const u32x4 w = *(const u32x4*)(stg + (row * 64 + ch * 8) * 2);
;             *(u32x4*)(Ow + (size_t)row * OP + hf * 64 + ch * 8) = w; }
;         asm volatile("s_waitcnt lgkmcnt(0)" ::: "memory"); }
	global_store_dwordx4 v[24:25], v[8:11], off nt
	s_nop 1
	v_add_u32_e32 v8, 16, v0
	v_lshlrev_b32_e32 v1, 7, v8
	v_add_u32_e32 v0, 24, v0
	v_add3_u32 v18, s91, v1, v12
	v_ashrrev_i32_e32 v9, 31, v8
	v_lshlrev_b32_e32 v1, 7, v0
	v_lshlrev_b64 v[8:9], 12, v[8:9]
	v_add3_u32 v19, s91, v1, v12
	ds_read_b128 v[4:7], v18 offset:32768
	v_lshl_add_u64 v[26:27], v[14:15], 0, v[8:9]
	ds_read_b128 v[8:11], v19 offset:32768
	v_ashrrev_i32_e32 v1, 31, v0
	v_lshlrev_b64 v[0:1], 12, v[0:1]
	v_lshl_add_u64 v[0:1], v[14:15], 0, v[0:1]
	s_waitcnt lgkmcnt(1)
	global_store_dwordx4 v[26:27], v[4:7], off nt
	s_waitcnt lgkmcnt(0)
	global_store_dwordx4 v[0:1], v[8:11], off nt
	s_waitcnt lgkmcnt(0)
	v_mul_f32_e32 v4, v50, v17
	v_cvt_pk_bf16_f32 v4, v4, v4
	ds_write_b16 v3, v4 offset:32768
	v_mul_f32_e32 v4, v34, v17
	v_cvt_pk_bf16_f32 v4, v4, v4
	ds_write_b16 v3, v4 offset:32832
	v_mul_f32_e32 v4, v51, v82
	v_cvt_pk_bf16_f32 v4, v4, v4
	ds_write_b16 v3, v4 offset:32896
	v_mul_f32_e32 v4, v35, v82
	v_cvt_pk_bf16_f32 v4, v4, v4
	ds_write_b16 v3, v4 offset:32960
	v_mul_f32_e32 v4, v52, v83
	v_cvt_pk_bf16_f32 v4, v4, v4
	ds_write_b16 v3, v4 offset:33024
	v_mul_f32_e32 v4, v36, v83
	v_cvt_pk_bf16_f32 v4, v4, v4
	ds_write_b16 v3, v4 offset:33088
	v_mul_f32_e32 v4, v53, v84
	v_cvt_pk_bf16_f32 v4, v4, v4
	ds_write_b16 v3, v4 offset:33152
	v_mul_f32_e32 v4, v37, v84
	v_cvt_pk_bf16_f32 v4, v4, v4
	ds_write_b16 v3, v4 offset:33216
	v_mul_f32_e32 v4, v54, v85
	v_cvt_pk_bf16_f32 v4, v4, v4
	ds_write_b16 v3, v4 offset:33792
	v_mul_f32_e32 v4, v38, v85
	v_cvt_pk_bf16_f32 v4, v4, v4
	ds_write_b16 v3, v4 offset:33856
	v_mul_f32_e32 v4, v55, v86
	v_cvt_pk_bf16_f32 v4, v4, v4
	ds_write_b16 v3, v4 offset:33920
	v_mul_f32_e32 v4, v39, v86
	v_cvt_pk_bf16_f32 v4, v4, v4
	ds_write_b16 v3, v4 offset:33984
	v_mul_f32_e32 v4, v56, v87
	v_cvt_pk_bf16_f32 v4, v4, v4
	ds_write_b16 v3, v4 offset:34048
	v_mul_f32_e32 v4, v40, v87
	v_cvt_pk_bf16_f32 v4, v4, v4
	ds_write_b16 v3, v4 offset:34112
	v_mul_f32_e32 v4, v57, v88
	v_cvt_pk_bf16_f32 v4, v4, v4
	ds_write_b16 v3, v4 offset:34176
	v_mul_f32_e32 v4, v41, v88
	v_cvt_pk_bf16_f32 v4, v4, v4
	ds_write_b16 v3, v4 offset:34240
	v_mul_f32_e32 v4, v58, v89
	v_cvt_pk_bf16_f32 v4, v4, v4
	ds_write_b16 v3, v4 offset:34816
	v_mul_f32_e32 v4, v42, v89
	v_cvt_pk_bf16_f32 v4, v4, v4
	ds_write_b16 v3, v4 offset:34880
	v_mul_f32_e32 v4, v59, v90
	v_cvt_pk_bf16_f32 v4, v4, v4
	ds_write_b16 v3, v4 offset:34944
	v_mul_f32_e32 v4, v43, v90
	v_cvt_pk_bf16_f32 v4, v4, v4
	ds_write_b16 v3, v4 offset:35008
	v_mul_f32_e32 v4, v60, v91
	v_cvt_pk_bf16_f32 v4, v4, v4
	ds_write_b16 v3, v4 offset:35072
	v_mul_f32_e32 v4, v44, v91
	v_cvt_pk_bf16_f32 v4, v4, v4
	ds_write_b16 v3, v4 offset:35136
	v_mul_f32_e32 v4, v61, v92
	v_cvt_pk_bf16_f32 v4, v4, v4
	ds_write_b16 v3, v4 offset:35200
	v_mul_f32_e32 v4, v45, v92
	v_cvt_pk_bf16_f32 v4, v4, v4
	ds_write_b16 v3, v4 offset:35264
	v_mul_f32_e32 v4, v62, v93
	v_cvt_pk_bf16_f32 v4, v4, v4
	ds_write_b16 v3, v4 offset:35840
	v_mul_f32_e32 v4, v46, v93
	v_cvt_pk_bf16_f32 v4, v4, v4
	ds_write_b16 v3, v4 offset:35904
	v_mul_f32_e32 v4, v63, v94
	v_cvt_pk_bf16_f32 v4, v4, v4
	ds_write_b16 v3, v4 offset:35968
	v_mul_f32_e32 v4, v47, v94
	v_cvt_pk_bf16_f32 v4, v4, v4
	ds_write_b16 v3, v4 offset:36032
	v_mul_f32_e32 v4, v64, v95
	v_cvt_pk_bf16_f32 v4, v4, v4
	ds_write_b16 v3, v4 offset:36096
	v_mul_f32_e32 v4, v48, v95
	v_cvt_pk_bf16_f32 v4, v4, v4
	ds_write_b16 v3, v4 offset:36160
	v_mul_f32_e32 v4, v65, v96
	v_cvt_pk_bf16_f32 v4, v4, v4
	ds_write_b16 v3, v4 offset:36224
	v_mul_f32_e32 v4, v49, v96
	v_cvt_pk_bf16_f32 v4, v4, v4
	ds_write_b16 v3, v4 offset:36288
	s_waitcnt lgkmcnt(0)
	ds_read_b128 v[4:7], v13 offset:32768
	ds_read_b128 v[8:11], v20 offset:32768
	ds_read_b128 v[12:15], v18 offset:32768
	ds_read_b128 v[18:21], v19 offset:32768
	s_waitcnt lgkmcnt(3)
	global_store_dwordx4 v[22:23], v[4:7], off offset:128 nt
	s_waitcnt lgkmcnt(2)
	global_store_dwordx4 v[24:25], v[8:11], off offset:128 nt
	s_waitcnt lgkmcnt(1)
	global_store_dwordx4 v[26:27], v[12:15], off offset:128 nt
	s_waitcnt lgkmcnt(0)
	global_store_dwordx4 v[0:1], v[18:21], off offset:128 nt
	s_waitcnt lgkmcnt(0)
	s_barrier
	s_branch .LBB0_784

; __device__ __forceinline__ int crow(int r, int hi) { return (r & 3) + 8 * (r >> 2) + 4 * hi; }
; __device__ __forceinline__ unsigned cvtpk(float lo, float hi) { unsigned r; asm volatile("v_cvt_pk_bf16_f32 %0, %1, %2" : "=v"(r) : "v"(lo), "v"(hi)); return r; }
; template <int OP>
; __device__ __forceinline__ void store_o_tile(const f32x16* o, const float* rli, char* stg, bf16_t* Ow, int r32e, int hie, int lane2) {
; #pragma unroll
;     for (int hf = 0; hf < 2; ++hf) {
; #pragma unroll
;         for (int r = 0; r < 16; ++r) { const int orow = crow(r, hie);
; #pragma unroll
;             for (int d = 0; d < 2; ++d) { const float v = o[2 * hf + d][r] * rli[r]; *(unsigned short*)(stg + (orow * 64 + d * 32 + r32e) * 2) = (unsigned short)cvtpk(v, v); } }
; template <int OP>
; __device__ __forceinline__ void attn_unit_x(const UnitX& u, char* lds, const int wid) {
;     ...
;     int lane2; asm volatile("v_mbcnt_lo_u32_b32 %0, -1, 0\n\tv_mbcnt_hi_u32_b32 %0, -1, %0" : "=v"(lane2));
;     const int r32e = lane2 & 31, hie = lane2 >> 5;
;     if (hie == 0) psc[vh * 64 + r32e] = l_reg;
;     asm volatile("s_waitcnt lgkmcnt(0)" ::: "memory"); __syncthreads();
;     float rli[16];
; #pragma unroll
;     for (int r = 0; r < 16; ++r) rli[r] = __builtin_amdgcn_rcpf(psc[crow(r, hie)] + psc[64 + crow(r, hie)]);
;     store_o_tile<OP>(o, rli, lds + XOFF_K + wid * 4096, u.O + (size_t)(g * QBLK) * OP + vh * 128, r32e, hie, lane2);
.LBB0_783:
	s_or_b64 exec, exec, s[4:5]
	v_ashrrev_i32_e32 v1, 5, v0
	v_lshl_add_u32 v3, v1, 4, s95
	s_waitcnt lgkmcnt(0)
	s_waitcnt lgkmcnt(0)
	s_barrier
	ds_read_b128 v[4:7], v3
	ds_read_b128 v[8:11], v3 offset:32
	ds_read_b128 v[12:15], v3 offset:256
	v_readlane_b32 s6, v254, 20
	s_cmp_eq_u32 s60, 0
	v_readlane_b32 s7, v254, 21
	s_cselect_b32 s4, s29, s7
	s_waitcnt lgkmcnt(0)
	v_add_f32_e32 v4, v4, v12
	v_rcp_f32_e32 v17, v4
	v_add_f32_e32 v4, v5, v13
	v_rcp_f32_e32 v20, v4
	v_add_f32_e32 v4, v6, v14
	v_rcp_f32_e32 v21, v4
	v_add_f32_e32 v4, v7, v15
	v_rcp_f32_e32 v22, v4
	ds_read_b128 v[4:7], v3 offset:288
	s_cselect_b32 s5, s28, s6
	s_lshl_b32 s6, s61, 12
	s_add_u32 s5, s5, s6
	s_addc_u32 s6, s4, 0
	s_waitcnt lgkmcnt(0)
	v_add_f32_e32 v4, v8, v4
	v_rcp_f32_e32 v23, v4
	v_add_f32_e32 v4, v9, v5
	v_rcp_f32_e32 v24, v4
	v_add_f32_e32 v4, v10, v6
	v_rcp_f32_e32 v25, v4
	v_add_f32_e32 v4, v11, v7
	v_rcp_f32_e32 v26, v4
	ds_read_b128 v[4:7], v3 offset:64
	ds_read_b128 v[8:11], v3 offset:320
	s_lshl_b32 s4, s42, 9
	s_add_u32 s4, s5, s4
	s_addc_u32 s5, s6, 0
	v_readlane_b32 s1, v254, 37
	s_waitcnt lgkmcnt(0)
	v_add_f32_e32 v4, v4, v8
	v_rcp_f32_e32 v27, v4
	v_add_f32_e32 v4, v5, v9
	v_rcp_f32_e32 v28, v4
	v_add_f32_e32 v4, v6, v10
	v_rcp_f32_e32 v29, v4
	v_add_f32_e32 v4, v7, v11
	v_rcp_f32_e32 v30, v4
	ds_read_b128 v[4:7], v3 offset:96
	ds_read_b128 v[8:11], v3 offset:352
	s_add_u32 s4, s4, s1
	s_addc_u32 s5, s5, 0
	v_readlane_b32 s1, v254, 38
	s_add_u32 s4, s4, s1
	s_waitcnt lgkmcnt(0)
	v_add_f32_e32 v3, v4, v8
	v_add_f32_e32 v4, v5, v9
	v_rcp_f32_e32 v31, v4
	v_add_f32_e32 v4, v6, v10
	v_rcp_f32_e32 v96, v4
	v_add_f32_e32 v4, v7, v11
	v_rcp_f32_e32 v97, v4
	v_ashrrev_i32_e32 v8, 3, v0
	v_lshlrev_b32_e32 v4, 4, v0
	v_lshlrev_b32_e32 v0, 1, v0
	s_addc_u32 s5, s5, 0
	v_and_b32_e32 v10, 0x70, v4
	v_mov_b32_e32 v11, v2
	v_lshlrev_b32_e32 v4, 7, v8
	v_lshlrev_b32_e32 v1, 9, v1
	v_and_b32_e32 v0, 62, v0
	v_lshl_add_u64 v[12:13], s[4:5], 0, v[10:11]
	v_add3_u32 v11, s8, v4, v10
	v_mul_f32_e32 v4, v80, v17
	v_add3_u32 v80, s8, v1, v0
	v_mul_f32_e32 v0, v64, v17
	v_cvt_pk_bf16_f32 v4, v4, v4
	ds_write_b16 v80, v4
	v_cvt_pk_bf16_f32 v0, v0, v0
	ds_write_b16 v80, v0 offset:64
	v_mul_f32_e32 v0, v81, v20
	v_cvt_pk_bf16_f32 v0, v0, v0
	ds_write_b16 v80, v0 offset:128
	v_mul_f32_e32 v0, v65, v20
	v_cvt_pk_bf16_f32 v0, v0, v0
	ds_write_b16 v80, v0 offset:192
	v_mul_f32_e32 v0, v82, v21
	v_cvt_pk_bf16_f32 v0, v0, v0
	ds_write_b16 v80, v0 offset:256
	v_mul_f32_e32 v0, v66, v21
	v_cvt_pk_bf16_f32 v0, v0, v0
	ds_write_b16 v80, v0 offset:320
	v_mul_f32_e32 v0, v83, v22
	v_cvt_pk_bf16_f32 v0, v0, v0
	ds_write_b16 v80, v0 offset:384
	v_mul_f32_e32 v0, v67, v22
	v_cvt_pk_bf16_f32 v0, v0, v0
	ds_write_b16 v80, v0 offset:448
	v_mul_f32_e32 v0, v84, v23
	v_cvt_pk_bf16_f32 v0, v0, v0
	ds_write_b16 v80, v0 offset:1024
	v_mul_f32_e32 v0, v68, v23
	v_cvt_pk_bf16_f32 v0, v0, v0
	ds_write_b16 v80, v0 offset:1088
	v_mul_f32_e32 v0, v85, v24
	v_cvt_pk_bf16_f32 v0, v0, v0
	ds_write_b16 v80, v0 offset:1152
	v_mul_f32_e32 v0, v69, v24
	v_cvt_pk_bf16_f32 v0, v0, v0
	ds_write_b16 v80, v0 offset:1216
	v_mul_f32_e32 v0, v86, v25
	v_cvt_pk_bf16_f32 v0, v0, v0
	ds_write_b16 v80, v0 offset:1280
	v_mul_f32_e32 v0, v70, v25
	v_cvt_pk_bf16_f32 v0, v0, v0
	ds_write_b16 v80, v0 offset:1344
	v_mul_f32_e32 v0, v87, v26
	v_cvt_pk_bf16_f32 v0, v0, v0
	ds_write_b16 v80, v0 offset:1408
	v_mul_f32_e32 v0, v71, v26
	v_cvt_pk_bf16_f32 v0, v0, v0
	ds_write_b16 v80, v0 offset:1472
	v_mul_f32_e32 v0, v88, v27
	v_cvt_pk_bf16_f32 v0, v0, v0
	ds_write_b16 v80, v0 offset:2048
	v_mul_f32_e32 v0, v72, v27
	v_cvt_pk_bf16_f32 v0, v0, v0
	ds_write_b16 v80, v0 offset:2112
	v_mul_f32_e32 v0, v89, v28
	v_cvt_pk_bf16_f32 v0, v0, v0
	ds_write_b16 v80, v0 offset:2176
	v_mul_f32_e32 v0, v73, v28
	v_cvt_pk_bf16_f32 v0, v0, v0
	ds_write_b16 v80, v0 offset:2240
	v_mul_f32_e32 v0, v90, v29
	v_cvt_pk_bf16_f32 v0, v0, v0
	ds_write_b16 v80, v0 offset:2304
	v_mul_f32_e32 v0, v74, v29
	v_cvt_pk_bf16_f32 v0, v0, v0
	v_rcp_f32_e32 v3, v3
	ds_write_b16 v80, v0 offset:2368
	v_mul_f32_e32 v0, v91, v30
	v_cvt_pk_bf16_f32 v0, v0, v0
	ds_write_b16 v80, v0 offset:2432
	v_mul_f32_e32 v0, v75, v30
	v_cvt_pk_bf16_f32 v0, v0, v0
	ds_write_b16 v80, v0 offset:2496
	v_mul_f32_e32 v0, v92, v3
	v_cvt_pk_bf16_f32 v0, v0, v0
	ds_write_b16 v80, v0 offset:3072
	v_mul_f32_e32 v0, v76, v3
	v_cvt_pk_bf16_f32 v0, v0, v0
	ds_write_b16 v80, v0 offset:3136
	v_mul_f32_e32 v0, v93, v31
	v_cvt_pk_bf16_f32 v0, v0, v0
	ds_write_b16 v80, v0 offset:3200
	v_mul_f32_e32 v0, v77, v31
	v_cvt_pk_bf16_f32 v0, v0, v0
	ds_write_b16 v80, v0 offset:3264
	v_mul_f32_e32 v0, v94, v96
	v_cvt_pk_bf16_f32 v0, v0, v0
	ds_write_b16 v80, v0 offset:3328
	v_mul_f32_e32 v0, v78, v96
	v_cvt_pk_bf16_f32 v0, v0, v0
	ds_write_b16 v80, v0 offset:3392
	v_mul_f32_e32 v0, v95, v97
	v_cvt_pk_bf16_f32 v0, v0, v0
	ds_write_b16 v80, v0 offset:3456
	v_mul_f32_e32 v0, v79, v97
	v_cvt_pk_bf16_f32 v0, v0, v0
	ds_write_b16 v80, v0 offset:3520
	s_waitcnt lgkmcnt(0)
; __device__ __forceinline__ unsigned cvtpk(float lo, float hi) { unsigned r; asm volatile("v_cvt_pk_bf16_f32 %0, %1, %2" : "=v"(r) : "v"(lo), "v"(hi)); return r; }
; template <int OP>
; __device__ __forceinline__ void store_o_tile(const f32x16* o, const float* rli, char* stg, bf16_t* Ow, int r32e, int hie, int lane2) {
;     ...
;             for (int d = 0; d < 2; ++d) { const float v = o[2 * hf + d][r] * rli[r]; *(unsigned short*)(stg + (orow * 64 + d * 32 + r32e) * 2) = (unsigned short)cvtpk(v, v); } }
;         asm volatile("s_waitcnt lgkmcnt(0)" ::: "memory");
; #pragma unroll
;         for (int i = 0; i < 4; ++i) { const int row = i * 8 + (lane2 >> 3), ch = lane2 & 7; const u32x4 w = *(const u32x4*)(stg + (row * 64 + ch * 8) * 2);
;             *(u32x4*)(Ow + (size_t)row * OP + hf * 64 + ch * 8) = w; }
;         asm volatile("s_waitcnt lgkmcnt(0)" ::: "memory"); }
	ds_read_b128 v[4:7], v11
	v_ashrrev_i32_e32 v9, 31, v8
	v_lshlrev_b64 v[0:1], 12, v[8:9]
	v_lshl_add_u64 v[0:1], v[12:13], 0, v[0:1]
	v_add_u32_e32 v14, 8, v8
	s_waitcnt lgkmcnt(0)
	global_store_dwordx4 v[0:1], v[4:7], off nt
	v_ashrrev_i32_e32 v15, 31, v14
	v_add_u32_e32 v18, 16, v8
	v_lshlrev_b32_e32 v4, 7, v14
	v_add3_u32 v64, s8, v4, v10
	ds_read_b128 v[4:7], v64
	v_lshlrev_b64 v[14:15], 12, v[14:15]
	v_lshl_add_u64 v[14:15], v[12:13], 0, v[14:15]
	v_ashrrev_i32_e32 v19, 31, v18
	v_add_u32_e32 v8, 24, v8
	s_waitcnt lgkmcnt(0)
	global_store_dwordx4 v[14:15], v[4:7], off nt
	v_ashrrev_i32_e32 v9, 31, v8
	s_nop 0
	v_lshlrev_b32_e32 v4, 7, v18
	v_add3_u32 v65, s8, v4, v10
	ds_read_b128 v[4:7], v65
	v_lshlrev_b64 v[18:19], 12, v[18:19]
	v_lshl_add_u64 v[18:19], v[12:13], 0, v[18:19]
	s_waitcnt lgkmcnt(0)
	global_store_dwordx4 v[18:19], v[4:7], off nt
	s_nop 1
	v_lshlrev_b32_e32 v4, 7, v8
	v_add3_u32 v10, s8, v4, v10
	ds_read_b128 v[4:7], v10
	v_lshlrev_b64 v[8:9], 12, v[8:9]
	v_lshl_add_u64 v[8:9], v[12:13], 0, v[8:9]
	s_waitcnt lgkmcnt(0)
	global_store_dwordx4 v[8:9], v[4:7], off nt
	s_nop 1
	v_mul_f32_e32 v4, v48, v17
	s_waitcnt lgkmcnt(0)
	v_cvt_pk_bf16_f32 v4, v4, v4
	ds_write_b16 v80, v4
	v_mul_f32_e32 v4, v32, v17
	v_cvt_pk_bf16_f32 v4, v4, v4
	ds_write_b16 v80, v4 offset:64
	v_mul_f32_e32 v4, v49, v20
	v_cvt_pk_bf16_f32 v4, v4, v4
	ds_write_b16 v80, v4 offset:128
	v_mul_f32_e32 v4, v33, v20
	v_cvt_pk_bf16_f32 v4, v4, v4
	ds_write_b16 v80, v4 offset:192
	v_mul_f32_e32 v4, v50, v21
	v_cvt_pk_bf16_f32 v4, v4, v4
	ds_write_b16 v80, v4 offset:256
	v_mul_f32_e32 v4, v34, v21
	v_cvt_pk_bf16_f32 v4, v4, v4
	ds_write_b16 v80, v4 offset:320
	v_mul_f32_e32 v4, v51, v22
	v_cvt_pk_bf16_f32 v4, v4, v4
	ds_write_b16 v80, v4 offset:384
	v_mul_f32_e32 v4, v35, v22
	v_cvt_pk_bf16_f32 v4, v4, v4
	ds_write_b16 v80, v4 offset:448
	v_mul_f32_e32 v4, v52, v23
	v_cvt_pk_bf16_f32 v4, v4, v4
	ds_write_b16 v80, v4 offset:1024
	v_mul_f32_e32 v4, v36, v23
	v_cvt_pk_bf16_f32 v4, v4, v4
	ds_write_b16 v80, v4 offset:1088
	v_mul_f32_e32 v4, v53, v24
	v_cvt_pk_bf16_f32 v4, v4, v4
	ds_write_b16 v80, v4 offset:1152
	v_mul_f32_e32 v4, v37, v24
	v_cvt_pk_bf16_f32 v4, v4, v4
	ds_write_b16 v80, v4 offset:1216
	v_mul_f32_e32 v4, v54, v25
	v_cvt_pk_bf16_f32 v4, v4, v4
	ds_write_b16 v80, v4 offset:1280
	v_mul_f32_e32 v4, v38, v25
	v_cvt_pk_bf16_f32 v4, v4, v4
	ds_write_b16 v80, v4 offset:1344
	v_mul_f32_e32 v4, v55, v26
	v_cvt_pk_bf16_f32 v4, v4, v4
	ds_write_b16 v80, v4 offset:1408
	v_mul_f32_e32 v4, v39, v26
	v_cvt_pk_bf16_f32 v4, v4, v4
	ds_write_b16 v80, v4 offset:1472
	v_mul_f32_e32 v4, v56, v27
	v_cvt_pk_bf16_f32 v4, v4, v4
	ds_write_b16 v80, v4 offset:2048
	v_mul_f32_e32 v4, v40, v27
	v_cvt_pk_bf16_f32 v4, v4, v4
	ds_write_b16 v80, v4 offset:2112
	v_mul_f32_e32 v4, v57, v28
	v_cvt_pk_bf16_f32 v4, v4, v4
	ds_write_b16 v80, v4 offset:2176
	v_mul_f32_e32 v4, v41, v28
	v_cvt_pk_bf16_f32 v4, v4, v4
	ds_write_b16 v80, v4 offset:2240
	v_mul_f32_e32 v4, v58, v29
	v_cvt_pk_bf16_f32 v4, v4, v4
	ds_write_b16 v80, v4 offset:2304
	v_mul_f32_e32 v4, v42, v29
	v_cvt_pk_bf16_f32 v4, v4, v4
	ds_write_b16 v80, v4 offset:2368
	v_mul_f32_e32 v4, v59, v30
	v_cvt_pk_bf16_f32 v4, v4, v4
	ds_write_b16 v80, v4 offset:2432
	v_mul_f32_e32 v4, v43, v30
	v_cvt_pk_bf16_f32 v4, v4, v4
	ds_write_b16 v80, v4 offset:2496
	v_mul_f32_e32 v4, v60, v3
	v_mul_f32_e32 v3, v44, v3
	v_cvt_pk_bf16_f32 v4, v4, v4
	ds_write_b16 v80, v4 offset:3072
	v_cvt_pk_bf16_f32 v3, v3, v3
	ds_write_b16 v80, v3 offset:3136
	v_mul_f32_e32 v3, v61, v31
	v_cvt_pk_bf16_f32 v3, v3, v3
	ds_write_b16 v80, v3 offset:3200
	v_mul_f32_e32 v3, v45, v31
	v_cvt_pk_bf16_f32 v3, v3, v3
	ds_write_b16 v80, v3 offset:3264
	v_mul_f32_e32 v3, v62, v96
	v_cvt_pk_bf16_f32 v3, v3, v3
	ds_write_b16 v80, v3 offset:3328
	v_mul_f32_e32 v3, v46, v96
	v_cvt_pk_bf16_f32 v3, v3, v3
	ds_write_b16 v80, v3 offset:3392
	v_mul_f32_e32 v3, v63, v97
	v_cvt_pk_bf16_f32 v3, v3, v3
	ds_write_b16 v80, v3 offset:3456
	v_mul_f32_e32 v3, v47, v97
	v_cvt_pk_bf16_f32 v3, v3, v3
	ds_write_b16 v80, v3 offset:3520
	s_waitcnt lgkmcnt(0)
	ds_read_b128 v[4:7], v11
	s_waitcnt lgkmcnt(0)
	global_store_dwordx4 v[0:1], v[4:7], off offset:128 nt
	ds_read_b128 v[4:7], v64
	s_waitcnt lgkmcnt(0)
	global_store_dwordx4 v[14:15], v[4:7], off offset:128 nt
	ds_read_b128 v[4:7], v65
	s_waitcnt lgkmcnt(0)
	global_store_dwordx4 v[18:19], v[4:7], off offset:128 nt
	ds_read_b128 v[4:7], v10
	s_waitcnt lgkmcnt(0)
	global_store_dwordx4 v[8:9], v[4:7], off offset:128 nt
	s_waitcnt lgkmcnt(0)
	s_waitcnt lgkmcnt(0)
	s_barrier
